# row passes (P4, P8): dropped the spurious vmcnt waits in front of each row's loads so the 4 rows of a group are in flight together (were fetched one after another)
# speedup vs baseline: 1.0252x; 1.0252x over previous
.LBB0_720:
	s_add_u32 s44, s10, s14
	s_cmp_gt_i32 s37, 0
	s_cselect_b64 s[6:7], -1, 0
	s_cmp_lt_i32 s37, 1
	s_cbranch_scc1 .LBB0_722
	s_add_u32 s26, s10, s14
	s_addc_u32 s27, s11, s15
	s_add_i32 s28, s44, 0xffff8000
	s_cmp_lt_i32 s44, 0x8000
	s_cselect_b32 s26, s26, s28
	s_cselect_b32 s28, 0, 8
	s_cselect_b32 s27, s27, 0
	s_add_u32 s28, s8, s28
	s_load_dwordx2 s[24:25], s[8:9], 0xc0
	s_addc_u32 s29, s9, 0
	s_load_dwordx2 s[28:29], s[28:29], 0x0
	s_waitcnt lgkmcnt(0)
	v_lshl_add_u64 v[18:19], s[24:25], 0, v[84:85]
	s_lshl_b64 s[24:25], s[26:27], 12
	s_add_u32 s24, s28, s24
	s_addc_u32 s25, s29, s25
	v_lshl_add_u64 v[122:123], v[82:83], 4, s[24:25]
	global_load_dwordx2 v[92:93], v[18:19], off offset:-1536 nt
	global_load_dwordx2 v[90:91], v[18:19], off offset:-1024 nt
	global_load_dwordx2 v[88:89], v[18:19], off offset:-512 nt
	global_load_dwordx2 v[86:87], v[18:19], off nt
	global_load_dwordx4 v[30:33], v[122:123], off nt
	global_load_dwordx4 v[26:29], v[122:123], off offset:1024 nt
	global_load_dwordx4 v[22:25], v[122:123], off offset:2048 nt
	s_nop 0
	global_load_dwordx4 v[18:21], v[122:123], off offset:3072 nt
.LBB0_722:
	s_cmp_gt_i32 s37, 1
	s_cselect_b64 s[28:29], -1, 0
	s_cmp_lt_i32 s37, 2
	s_cbranch_scc1 .LBB0_731
	s_load_dwordx2 s[24:25], s[8:9], 0xc0
	s_add_i32 s26, s44, 1
	s_ashr_i32 s27, s26, 31
	s_lshl_b64 s[30:31], s[26:27], 11
	s_waitcnt lgkmcnt(0)
	s_add_u32 s24, s24, s30
	s_addc_u32 s25, s25, s31
	v_lshl_add_u64 v[66:67], v[82:83], 3, s[24:25]
	s_add_i32 s24, s44, 0xffff8001
	s_cmpk_lt_i32 s44, 0x7fff
	s_cselect_b32 s24, s26, s24
	s_cselect_b32 s26, 0, 8
	s_cselect_b32 s25, s27, 0
	s_add_u32 s26, s8, s26
	s_addc_u32 s27, s9, 0
	s_load_dwordx2 s[26:27], s[26:27], 0x0
	s_lshl_b64 s[24:25], s[24:25], 12
	v_lshl_add_u64 v[68:69], v[66:67], 0, s[16:17]
	v_add_co_u32_e32 v66, vcc, s38, v66
	s_waitcnt lgkmcnt(0)
	s_add_u32 s24, s26, s24
	s_addc_u32 s25, s27, s25
	v_addc_co_u32_e32 v67, vcc, 0, v67, vcc
	v_lshl_add_u64 v[122:123], v[82:83], 4, s[24:25]
	global_load_dwordx2 v[116:117], v[66:67], off nt
	global_load_dwordx2 v[114:115], v[68:69], off offset:512 nt
	global_load_dwordx2 v[112:113], v[68:69], off offset:1024 nt
	global_load_dwordx2 v[110:111], v[68:69], off offset:1536 nt
	global_load_dwordx4 v[78:81], v[122:123], off nt
	global_load_dwordx4 v[74:77], v[122:123], off offset:1024 nt
	global_load_dwordx4 v[70:73], v[122:123], off offset:2048 nt
	s_nop 0
	global_load_dwordx4 v[66:69], v[122:123], off offset:3072 nt
	s_cmp_gt_i32 s37, 2
	s_cselect_b64 s[26:27], -1, 0
	s_cmp_lt_i32 s37, 3
	s_cbranch_scc0 .LBB0_732

.LBB0_725:
	s_load_dwordx2 s[30:31], s[8:9], 0xc0
	s_add_i32 s46, s44, 3
	s_ashr_i32 s47, s46, 31
	s_lshl_b64 s[48:49], s[46:47], 11
	s_waitcnt lgkmcnt(0)
	s_add_u32 s30, s30, s48
	s_addc_u32 s31, s31, s49
	v_lshl_add_u64 v[34:35], v[82:83], 3, s[30:31]
	s_add_i32 s30, s44, 0xffff8003
	s_cmpk_lt_i32 s44, 0x7ffd
	s_cselect_b32 s45, 0, 8
	s_cselect_b32 s31, s47, 0
	s_cselect_b32 s30, s46, s30
	s_add_u32 s46, s8, s45
	s_addc_u32 s47, s9, 0
	s_load_dwordx2 s[46:47], s[46:47], 0x0
	s_lshl_b64 s[30:31], s[30:31], 12
	v_lshl_add_u64 v[36:37], v[34:35], 0, s[16:17]
	v_add_co_u32_e32 v34, vcc, s38, v34
	s_waitcnt lgkmcnt(0)
	s_add_u32 s30, s46, s30
	v_addc_co_u32_e32 v35, vcc, 0, v35, vcc
	s_addc_u32 s31, s47, s31
	global_load_dwordx2 v[100:101], v[34:35], off nt
	global_load_dwordx2 v[98:99], v[36:37], off offset:512 nt
	global_load_dwordx2 v[96:97], v[36:37], off offset:1024 nt
	global_load_dwordx2 v[94:95], v[36:37], off offset:1536 nt
	v_lshl_add_u64 v[34:35], v[82:83], 4, s[30:31]
	global_load_dwordx4 v[46:49], v[34:35], off nt
	global_load_dwordx4 v[42:45], v[34:35], off offset:1024 nt
	global_load_dwordx4 v[38:41], v[34:35], off offset:2048 nt
	s_nop 0
	global_load_dwordx4 v[34:37], v[34:35], off offset:3072 nt
	s_andn2_b64 vcc, exec, s[6:7]
	s_cbranch_vccz .LBB0_734

.LBB0_732:
	s_load_dwordx2 s[24:25], s[8:9], 0xc0
	s_add_i32 s30, s44, 2
	s_ashr_i32 s31, s30, 31
	s_lshl_b64 s[46:47], s[30:31], 11
	s_waitcnt lgkmcnt(0)
	s_add_u32 s24, s24, s46
	s_addc_u32 s25, s25, s47
	v_lshl_add_u64 v[50:51], v[82:83], 3, s[24:25]
	s_add_i32 s24, s44, 0xffff8002
	s_cmpk_lt_i32 s44, 0x7ffe
	s_cselect_b32 s24, s30, s24
	s_cselect_b32 s30, 0, 8
	s_cselect_b32 s25, s31, 0
	s_add_u32 s30, s8, s30
	s_addc_u32 s31, s9, 0
	s_load_dwordx2 s[30:31], s[30:31], 0x0
	s_lshl_b64 s[24:25], s[24:25], 12
	v_lshl_add_u64 v[52:53], v[50:51], 0, s[16:17]
	v_add_co_u32_e32 v50, vcc, s38, v50
	s_waitcnt lgkmcnt(0)
	s_add_u32 s24, s30, s24
	s_addc_u32 s25, s31, s25
	v_addc_co_u32_e32 v51, vcc, 0, v51, vcc
	v_lshl_add_u64 v[122:123], v[82:83], 4, s[24:25]
	global_load_dwordx2 v[108:109], v[50:51], off nt
	global_load_dwordx2 v[106:107], v[52:53], off offset:512 nt
	global_load_dwordx2 v[104:105], v[52:53], off offset:1024 nt
	global_load_dwordx2 v[102:103], v[52:53], off offset:1536 nt
	global_load_dwordx4 v[62:65], v[122:123], off nt
	global_load_dwordx4 v[58:61], v[122:123], off offset:1024 nt
	global_load_dwordx4 v[54:57], v[122:123], off offset:2048 nt
	s_nop 0
	global_load_dwordx4 v[50:53], v[122:123], off offset:3072 nt
	s_cmp_gt_i32 s37, 3
	s_cselect_b64 s[24:25], -1, 0
	s_cmp_lt_i32 s37, 4
	s_cbranch_scc0 .LBB0_725

.LBB0_1081:
	s_cmp_gt_i32 s29, 0
	s_cselect_b64 s[2:3], -1, 0
	s_cmp_lt_i32 s29, 1
	s_cbranch_scc1 .LBB0_1083
	s_load_dwordx2 s[22:23], s[0:1], 0xc0
	s_waitcnt lgkmcnt(0)
	v_lshl_add_u64 v[46:47], s[22:23], 0, v[16:17]
	v_add_co_u32_e32 v94, vcc, 0xf7a00000, v46
	global_load_dwordx2 v[26:27], v[46:47], off offset:-1536 nt
	global_load_dwordx2 v[24:25], v[46:47], off offset:-1024 nt
	global_load_dwordx2 v[22:23], v[46:47], off offset:-512 nt
	global_load_dwordx2 v[20:21], v[46:47], off nt
	v_addc_co_u32_e32 v95, vcc, -1, v47, vcc
	global_load_dwordx2 v[52:53], v[94:95], off offset:-1536 nt
	global_load_dwordx2 v[50:51], v[94:95], off offset:-1024 nt
	global_load_dwordx2 v[48:49], v[94:95], off offset:-512 nt
	global_load_dwordx2 v[46:47], v[94:95], off nt
	s_add_u32 s22, s22, s5
	s_addc_u32 s23, s23, s28
	global_load_dword v76, v77, s[22:23]
.LBB0_1083:
	s_cmp_gt_i32 s29, 1
	s_cselect_b64 s[26:27], -1, 0
	s_cmp_lt_i32 s29, 2
	s_cbranch_scc1 .LBB0_1087
	s_load_dwordx2 s[22:23], s[0:1], 0xc0
	s_ashr_i32 s9, s8, 31
	s_lshl_b64 s[24:25], s[8:9], 11
	s_waitcnt lgkmcnt(0)
	s_add_u32 s24, s22, s24
	s_addc_u32 s25, s23, s25
	v_lshl_add_u64 v[78:79], v[184:185], 3, s[24:25]
	v_add_co_u32_e32 v82, vcc, 0x9700000, v78
	v_lshl_add_u64 v[80:81], v[78:79], 0, s[6:7]
	s_nop 0
	v_addc_co_u32_e32 v83, vcc, 0, v79, vcc
	v_add_co_u32_e32 v96, vcc, 0x1100000, v78
	s_lshl_b64 s[24:25], s[8:9], 2
	s_nop 0
	v_addc_co_u32_e32 v97, vcc, 0, v79, vcc
	global_load_dwordx2 v[34:35], v[82:83], off nt
	global_load_dwordx2 v[32:33], v[80:81], off offset:512 nt
	global_load_dwordx2 v[30:31], v[80:81], off offset:1024 nt
	global_load_dwordx2 v[28:29], v[80:81], off offset:1536 nt
	v_lshl_add_u64 v[94:95], v[78:79], 0, s[10:11]
	global_load_dwordx2 v[84:85], v[96:97], off nt
	global_load_dwordx2 v[82:83], v[94:95], off offset:512 nt
	global_load_dwordx2 v[80:81], v[94:95], off offset:1024 nt
	global_load_dwordx2 v[78:79], v[94:95], off offset:1536 nt
	s_add_u32 s22, s22, s24
	s_addc_u32 s23, s23, s25
	global_load_dword v86, v87, s[22:23]
	s_cmp_gt_i32 s29, 2
	s_cselect_b64 s[24:25], -1, 0
	s_cmp_lt_i32 s29, 3
	s_cbranch_scc0 .LBB0_1088

.LBB0_1086:
	s_load_dwordx2 s[34:35], s[0:1], 0xc0
	s_add_i32 s36, s8, 2
	s_ashr_i32 s37, s36, 31
	s_lshl_b64 s[38:39], s[36:37], 11
	s_waitcnt lgkmcnt(0)
	s_add_u32 s38, s34, s38
	s_addc_u32 s39, s35, s39
	v_lshl_add_u64 v[36:37], v[184:185], 3, s[38:39]
	v_add_co_u32_e32 v40, vcc, 0x9700000, v36
	s_lshl_b64 s[36:37], s[36:37], 2
	s_nop 0
	v_addc_co_u32_e32 v41, vcc, 0, v37, vcc
	v_add_co_u32_e32 v44, vcc, 0x1100000, v36
	v_lshl_add_u64 v[94:95], v[36:37], 0, s[6:7]
	s_nop 0
	v_addc_co_u32_e32 v45, vcc, 0, v37, vcc
	v_lshl_add_u64 v[42:43], v[36:37], 0, s[10:11]
	global_load_dwordx2 v[60:61], v[44:45], off nt
	global_load_dwordx2 v[36:37], v[40:41], off nt
	global_load_dwordx2 v[66:67], v[42:43], off offset:512 nt
	global_load_dwordx2 v[64:65], v[42:43], off offset:1024 nt
	global_load_dwordx2 v[62:63], v[42:43], off offset:1536 nt
	s_add_u32 s34, s34, s36
	s_addc_u32 s35, s35, s37
	global_load_dwordx2 v[44:45], v[94:95], off offset:512 nt
	global_load_dwordx2 v[42:43], v[94:95], off offset:1024 nt
	global_load_dwordx2 v[40:41], v[94:95], off offset:1536 nt
	global_load_dword v88, v87, s[34:35]
	s_andn2_b64 vcc, exec, s[2:3]
	v_mbcnt_hi_u32_b32 v93, -1, v92
	s_cbranch_vccz .LBB0_1090
	s_branch .LBB0_1091

.LBB0_1088:
	s_load_dwordx2 s[22:23], s[0:1], 0xc0
	s_add_i32 s34, s8, 1
	s_ashr_i32 s35, s34, 31
	s_lshl_b64 s[36:37], s[34:35], 11
	s_waitcnt lgkmcnt(0)
	s_add_u32 s36, s22, s36
	s_addc_u32 s37, s23, s37
	v_lshl_add_u64 v[38:39], v[184:185], 3, s[36:37]
	v_add_co_u32_e32 v54, vcc, 0x9700000, v38
	s_lshl_b64 s[34:35], s[34:35], 2
	s_nop 0
	v_addc_co_u32_e32 v55, vcc, 0, v39, vcc
	v_add_co_u32_e32 v58, vcc, 0x1100000, v38
	v_lshl_add_u64 v[94:95], v[38:39], 0, s[6:7]
	s_nop 0
	v_addc_co_u32_e32 v59, vcc, 0, v39, vcc
	v_lshl_add_u64 v[56:57], v[38:39], 0, s[10:11]
	global_load_dwordx2 v[68:69], v[58:59], off nt
	global_load_dwordx2 v[38:39], v[54:55], off nt
	global_load_dwordx2 v[74:75], v[56:57], off offset:512 nt
	global_load_dwordx2 v[72:73], v[56:57], off offset:1024 nt
	global_load_dwordx2 v[70:71], v[56:57], off offset:1536 nt
	s_add_u32 s22, s22, s34
	s_addc_u32 s23, s23, s35
	global_load_dwordx2 v[58:59], v[94:95], off offset:512 nt
	global_load_dwordx2 v[56:57], v[94:95], off offset:1024 nt
	global_load_dwordx2 v[54:55], v[94:95], off offset:1536 nt
	global_load_dword v90, v87, s[22:23]
	s_cmp_gt_i32 s29, 3
	s_cselect_b64 s[22:23], -1, 0
	s_cmp_lt_i32 s29, 4
	s_cbranch_scc0 .LBB0_1086
